# small per-step desynchronisation (s_sleep 2 after each step barrier, trailing virtual block only) in the stick-breaking and forgetting attention loops
# speedup vs baseline: 1.0039x; 1.0039x over previous
; DI float fexp2(float x) { return __builtin_amdgcn_exp2f(x); }
; template <int TYPE>
; DI void attn_item(KargPtr p, int b, int h, int qb, unsigned char* smem) {
;     ...
;         if (need) {
;             f32x16 s0, s1;
; #pragma unroll
;             for (int i = 0; i < 16; ++i) { s0[i] = 0.f; s1[i] = 0.f; }
; #pragma unroll
;             for (int ks = 0; ks < KS; ++ks) {
;                 const bf16x8 a0 = *(const bf16x8*)(kb + r * KROWB + ks * 32 + hh * 16);
;                 const bf16x8 a1 = *(const bf16x8*)(kb + (32 + r) * KROWB + ks * 32 + hh * 16);
;                 s0 = MFMA(a0, qfrag[ks], s0); s1 = MFMA(a1, qfrag[ks], s1);
;             }
;             if (TYPE != 2) {
;                 if (TYPE == 0) {
;                     if (k0 + 63 > qw) {
;                         asm volatile("");
;                         const int rel = myq - k0 - 4 * hh;
; #pragma unroll
;                         for (int i = 0; i < 16; ++i) {
;                             const int off = 8 * (i >> 2) + (i & 3);
;                             if (off > rel) s0[i] = -1e30f;
;                             if (off + 32 > rel) s1[i] = -1e30f;
;                         }
;                     }
;                 }
;                 float mx = s0[0];
; #pragma unroll
;                 for (int i = 1; i < 16; ++i) mx = fmaxf(mx, s0[i]);
; #pragma unroll
;                 for (int i = 0; i < 16; ++i) mx = fmaxf(mx, s1[i]);
;                 mx = fmaxf(mx, __shfl_xor(mx, 32));
;                 const float mnew = fmaxf(m, mx);
;                 const float alpha = fexp2(m - mnew);
;                 m = mnew;
;                 float ps = 0.f;
; #pragma unroll
;                 for (int i = 0; i < 16; i += 2) {
;                     const f32x2_t mm = {mnew, mnew};
;                     const f32x2_t d0 = (f32x2_t){s0[i], s0[i + 1]} - mm, d1 = (f32x2_t){s1[i], s1[i + 1]} - mm;
;                     s0[i] = fexp2(d0[0]); s0[i + 1] = fexp2(d0[1]); s1[i] = fexp2(d1[0]); s1[i + 1] = fexp2(d1[1]);
;                     ps += (s0[i] + s0[i + 1]) + (s1[i] + s1[i + 1]);
;                 }
;                 lsum = lsum * alpha + ps;
; #pragma unroll
;                 for (int i = 0; i < 16; ++i) { o0[i] *= alpha; o1[i] *= alpha; }
;             } else {
;                 float lk0[16], lk1[16];
; #pragma unroll
;                 for (int i = 0; i < 16; ++i) {
;                     {
.LBB0_576:
	s_or_b64 exec, exec, s[82:83]
	v_cmp_gt_f32_e32 vcc, s60, v164
	s_waitcnt vmcnt(4)
	v_add_u32_e32 v0, 0x6800, v214
	s_cmp_eq_u64 vcc, exec
	ds_write_b128 v212, v[106:109] offset:18688
	ds_write_b128 v213, v[110:113] offset:18688
	ds_write2_b64 v0, v[114:115], v[116:117] offset0:160 offset1:162
	v_add_u32_e32 v0, 0x6800, v216
	s_cselect_b64 s[8:9], -1, 0
	ds_write2_b64 v0, v[118:119], v[120:121] offset0:160 offset1:162
	s_and_saveexec_b64 s[10:11], s[6:7]
	v_cndmask_b32_e64 v0, 0, 1, s[8:9]
	ds_write_b32 v222, v0
	s_or_b64 exec, exec, s[10:11]
	v_mov_b32_e32 v0, s86
	s_waitcnt lgkmcnt(0)
	s_barrier
	s_cmp_eq_u32 s3, 0
	s_cbranch_scc1 .Ldesync_3
	s_sleep 2
.Ldesync_3:
	ds_read_b128 v[4:7], v0
	v_mov_b32_e32 v1, s77
	s_waitcnt lgkmcnt(0)
	v_and_b32_e32 v0, v5, v4
	v_and_b32_e32 v0, v0, v6
	v_and_b32_e32 v0, v0, v7
	ds_read_b128 v[4:7], v1
	s_waitcnt lgkmcnt(0)
	v_and_b32_e32 v0, v0, v4
	v_and_b32_e32 v0, v0, v5
	v_and_b32_e32 v0, v0, v6
	v_and_b32_e32 v0, v0, v7
	v_cmp_ne_u32_e32 vcc, 0, v0
	s_cbranch_vccnz .LBB0_571
	s_add_i32 s33, s78, 3
	s_cmp_lt_u32 s33, s76
	s_cselect_b32 s10, s2, 0
	v_add_u32_e32 v0, s10, v157
	v_ashrrev_i32_e32 v1, 31, v0
	v_lshlrev_b64 v[0:1], 10, v[0:1]
	v_lshl_add_u64 v[0:1], s[72:73], 0, v[0:1]
	v_lshl_add_u64 v[0:1], v[0:1], 0, v[2:3]
	global_load_dwordx4 v[106:109], v[0:1], off
	v_add_u32_e32 v0, s10, v211
	v_ashrrev_i32_e32 v1, 31, v0
	s_ashr_i32 s11, s10, 31
	v_lshlrev_b64 v[0:1], 10, v[0:1]
	s_lshl_b64 s[10:11], s[10:11], 7
	v_lshl_add_u64 v[0:1], s[72:73], 0, v[0:1]
	s_add_u32 s10, s87, s10
	v_lshl_add_u64 v[0:1], v[0:1], 0, v[2:3]
	s_addc_u32 s11, s75, s11
	global_load_dwordx4 v[110:113], v[0:1], off
	v_lshl_add_u64 v[0:1], v[160:161], 1, s[10:11]
	v_lshl_add_u64 v[0:1], v[0:1], 0, v[2:3]
	global_load_dwordx4 v[114:117], v[0:1], off
	v_lshl_add_u64 v[0:1], v[162:163], 1, s[10:11]
	v_lshl_add_u64 v[0:1], v[0:1], 0, v[2:3]
	global_load_dwordx4 v[118:121], v[0:1], off
	s_add_i32 s10, s2, 0x80
	v_cmp_le_i32_e32 vcc, s10, v219
	s_xor_b64 s[8:9], s[8:9], -1
	s_and_b64 s[8:9], vcc, s[8:9]
	s_and_saveexec_b64 s[82:83], s[8:9]
	s_cbranch_execz .LBB0_583
	v_add_u32_e32 v224, v220, v156
	ds_read_b128 v[4:7], v224 offset:18688
	ds_read_b128 v[8:11], v224 offset:18720
	s_add_i32 s8, s2, 0xbf
	v_cmp_ge_i32_e32 vcc, s8, v159
	s_waitcnt lgkmcnt(1)
	v_mfma_f32_32x32x16_bf16 v[50:65], v[4:7], v[86:89], 0
	ds_read_b128 v[4:7], v224 offset:23296
	ds_read_b128 v[12:15], v224 offset:23328
	s_waitcnt lgkmcnt(1)
	v_mfma_f32_32x32x16_bf16 v[66:81], v[4:7], v[86:89], 0
	s_nop 0
	v_mfma_f32_32x32x16_bf16 v[50:65], v[8:11], v[90:93], v[50:65]
	ds_read_b128 v[4:7], v224 offset:18752
	ds_read_b128 v[8:11], v224 offset:18784
	s_waitcnt lgkmcnt(2)
	v_mfma_f32_32x32x16_bf16 v[66:81], v[12:15], v[90:93], v[66:81]
	s_waitcnt lgkmcnt(1)
	v_mfma_f32_32x32x16_bf16 v[50:65], v[4:7], v[94:97], v[50:65]
	ds_read_b128 v[4:7], v224 offset:23360
	ds_read_b128 v[12:15], v224 offset:23392
	s_waitcnt lgkmcnt(1)
	v_mfma_f32_32x32x16_bf16 v[66:81], v[4:7], v[94:97], v[66:81]
	s_waitcnt lgkmcnt(0)
	v_mfma_f32_32x32x16_bf16 v[66:81], v[12:15], v[98:101], v[66:81]
	v_mfma_f32_32x32x16_bf16 v[50:65], v[8:11], v[98:101], v[50:65]
	s_nop 10
	v_exp_f32_e64 v1, -|v66|
	s_nop 0
	v_add_f32_e32 v1, 1.0, v1
	v_log_f32_e32 v6, v1
	v_max_f32_e32 v1, v66, v66
	v_max_f32_e32 v2, v50, v50
	v_exp_f32_e64 v0, -|v50|
	v_min_f32_e32 v4, 0, v2
	v_exp_f32_e64 v2, -|v51|
	v_min_f32_e32 v8, 0, v1
	v_add_f32_e32 v0, 1.0, v0
	v_log_f32_e32 v0, v0
	v_add_f32_e32 v1, 1.0, v2
	v_log_f32_e32 v1, v1
	v_exp_f32_e64 v2, -|v67|
	v_max_f32_e32 v5, v51, v51
	v_min_f32_e32 v5, 0, v5
	v_pk_add_f32 v[166:167], v[4:5], v[0:1] neg_lo:[0,1] neg_hi:[0,1]
	v_max_f32_e32 v1, v67, v67
	v_add_f32_e32 v0, 1.0, v2
	v_min_f32_e32 v9, 0, v1
	v_exp_f32_e64 v1, -|v68|
	v_log_f32_e32 v7, v0
	v_max_f32_e32 v2, v52, v52
	v_exp_f32_e64 v0, -|v52|
	v_min_f32_e32 v4, 0, v2
	v_exp_f32_e64 v2, -|v53|
	v_add_f32_e32 v1, 1.0, v1
	v_pk_add_f32 v[180:181], v[8:9], v[6:7] neg_lo:[0,1] neg_hi:[0,1]
	v_log_f32_e32 v6, v1
	v_max_f32_e32 v1, v68, v68
	v_add_f32_e32 v0, 1.0, v0
	v_min_f32_e32 v8, 0, v1
	v_add_f32_e32 v1, 1.0, v2
	v_log_f32_e32 v0, v0
	v_log_f32_e32 v1, v1
	v_exp_f32_e64 v2, -|v69|
	v_max_f32_e32 v5, v53, v53
	v_min_f32_e32 v5, 0, v5
	v_pk_add_f32 v[168:169], v[4:5], v[0:1] neg_lo:[0,1] neg_hi:[0,1]
	v_max_f32_e32 v1, v69, v69
	v_add_f32_e32 v0, 1.0, v2
	v_min_f32_e32 v9, 0, v1
	v_exp_f32_e64 v1, -|v70|
	v_log_f32_e32 v7, v0
	v_max_f32_e32 v2, v54, v54
	v_exp_f32_e64 v0, -|v54|
	v_min_f32_e32 v4, 0, v2
	v_exp_f32_e64 v2, -|v55|
	v_add_f32_e32 v1, 1.0, v1
	v_pk_add_f32 v[184:185], v[8:9], v[6:7] neg_lo:[0,1] neg_hi:[0,1]
	v_log_f32_e32 v6, v1
	v_max_f32_e32 v1, v70, v70
	v_add_f32_e32 v0, 1.0, v0
	v_min_f32_e32 v8, 0, v1
	v_add_f32_e32 v1, 1.0, v2
	v_log_f32_e32 v0, v0
	v_log_f32_e32 v1, v1
	v_exp_f32_e64 v2, -|v71|
	v_max_f32_e32 v5, v55, v55
	v_min_f32_e32 v5, 0, v5
	v_pk_add_f32 v[170:171], v[4:5], v[0:1] neg_lo:[0,1] neg_hi:[0,1]
	v_max_f32_e32 v1, v71, v71
	v_add_f32_e32 v0, 1.0, v2
	v_min_f32_e32 v9, 0, v1
	v_exp_f32_e64 v1, -|v72|
	v_log_f32_e32 v7, v0
	v_max_f32_e32 v2, v56, v56
	v_exp_f32_e64 v0, -|v56|
	v_min_f32_e32 v4, 0, v2
	v_exp_f32_e64 v2, -|v57|
	v_add_f32_e32 v1, 1.0, v1
	v_pk_add_f32 v[186:187], v[8:9], v[6:7] neg_lo:[0,1] neg_hi:[0,1]
	v_log_f32_e32 v6, v1
	v_max_f32_e32 v1, v72, v72
	v_add_f32_e32 v0, 1.0, v0
	v_min_f32_e32 v8, 0, v1
	v_add_f32_e32 v1, 1.0, v2
	v_log_f32_e32 v0, v0
	v_log_f32_e32 v1, v1
	v_exp_f32_e64 v2, -|v73|
	v_max_f32_e32 v5, v57, v57
	v_min_f32_e32 v5, 0, v5
	v_pk_add_f32 v[172:173], v[4:5], v[0:1] neg_lo:[0,1] neg_hi:[0,1]
	v_max_f32_e32 v1, v73, v73
; DI float fexp2(float x) { return __builtin_amdgcn_exp2f(x); }
; DI float flog2(float x) { return __builtin_amdgcn_logf(x); }
; template <int TYPE>
; DI void attn_item(KargPtr p, int b, int h, int qb, unsigned char* smem) {
;     ...
;                 float lk0[16], lk1[16];
; #pragma unroll
;                 for (int i = 0; i < 16; ++i) {
;                     {
;                         const float z = s0[i]; const float sp = flog2(1.0f + fexp2(-fabsf(z)));
;                         const float lb = fminf(z, 0.f) - sp;
;                         s0[i] = lb; lk0[i] = lb - z;
;                     }
;                     {
;                         const float z = s1[i]; const float sp = flog2(1.0f + fexp2(-fabsf(z)));
;                         const float lb = fminf(z, 0.f) - sp;
;                         s1[i] = lb; lk1[i] = lb - z;
;                     }
;                 }
	v_add_f32_e32 v0, 1.0, v2
	v_min_f32_e32 v9, 0, v1
	v_exp_f32_e64 v1, -|v74|
	v_log_f32_e32 v7, v0
	v_max_f32_e32 v2, v58, v58
	v_exp_f32_e64 v0, -|v58|
	v_min_f32_e32 v4, 0, v2
	v_exp_f32_e64 v2, -|v59|
	v_add_f32_e32 v1, 1.0, v1
	v_pk_add_f32 v[188:189], v[8:9], v[6:7] neg_lo:[0,1] neg_hi:[0,1]
	v_log_f32_e32 v6, v1
	v_max_f32_e32 v1, v74, v74
	v_add_f32_e32 v0, 1.0, v0
	v_min_f32_e32 v8, 0, v1
	v_add_f32_e32 v1, 1.0, v2
	v_log_f32_e32 v0, v0
	v_log_f32_e32 v1, v1
	v_exp_f32_e64 v2, -|v75|
	v_max_f32_e32 v5, v59, v59
	v_min_f32_e32 v5, 0, v5
	v_pk_add_f32 v[174:175], v[4:5], v[0:1] neg_lo:[0,1] neg_hi:[0,1]
	v_max_f32_e32 v1, v75, v75
	v_add_f32_e32 v0, 1.0, v2
	v_min_f32_e32 v9, 0, v1
	v_exp_f32_e64 v1, -|v76|
	v_log_f32_e32 v7, v0
	v_max_f32_e32 v2, v60, v60
	v_exp_f32_e64 v0, -|v60|
	v_min_f32_e32 v4, 0, v2
	v_exp_f32_e64 v2, -|v61|
	v_add_f32_e32 v1, 1.0, v1
	v_pk_add_f32 v[190:191], v[8:9], v[6:7] neg_lo:[0,1] neg_hi:[0,1]
	v_log_f32_e32 v6, v1
	v_max_f32_e32 v1, v76, v76
	v_add_f32_e32 v0, 1.0, v0
	v_min_f32_e32 v8, 0, v1
	v_add_f32_e32 v1, 1.0, v2
	v_log_f32_e32 v0, v0
	v_log_f32_e32 v1, v1
	v_exp_f32_e64 v2, -|v77|
	v_max_f32_e32 v5, v61, v61
	v_min_f32_e32 v5, 0, v5
	v_pk_add_f32 v[176:177], v[4:5], v[0:1] neg_lo:[0,1] neg_hi:[0,1]
	v_max_f32_e32 v1, v77, v77
	v_add_f32_e32 v0, 1.0, v2
	v_min_f32_e32 v9, 0, v1
	v_exp_f32_e64 v1, -|v78|
	v_log_f32_e32 v7, v0
	v_max_f32_e32 v2, v62, v62
	v_exp_f32_e64 v0, -|v62|
	v_min_f32_e32 v4, 0, v2
	v_exp_f32_e64 v2, -|v63|
	v_add_f32_e32 v1, 1.0, v1
	v_pk_add_f32 v[192:193], v[8:9], v[6:7] neg_lo:[0,1] neg_hi:[0,1]
	v_log_f32_e32 v6, v1
	v_max_f32_e32 v1, v78, v78
	v_add_f32_e32 v0, 1.0, v0
	v_min_f32_e32 v8, 0, v1
	v_add_f32_e32 v1, 1.0, v2
	v_log_f32_e32 v0, v0
	v_log_f32_e32 v1, v1
	v_exp_f32_e64 v2, -|v79|
	v_max_f32_e32 v5, v63, v63
	v_min_f32_e32 v5, 0, v5
	v_pk_add_f32 v[178:179], v[4:5], v[0:1] neg_lo:[0,1] neg_hi:[0,1]
	v_max_f32_e32 v1, v79, v79
	v_add_f32_e32 v0, 1.0, v2
	v_min_f32_e32 v9, 0, v1
	v_exp_f32_e64 v1, -|v80|
	v_max_f32_e32 v2, v64, v64
	v_log_f32_e32 v7, v0
	v_exp_f32_e64 v0, -|v64|
	v_min_f32_e32 v4, 0, v2
	v_exp_f32_e64 v2, -|v65|
	v_add_f32_e32 v1, 1.0, v1
	v_add_f32_e32 v0, 1.0, v0
	v_log_f32_e32 v138, v1
	v_add_f32_e32 v1, 1.0, v2
	v_log_f32_e32 v0, v0
	v_log_f32_e32 v1, v1
	v_max_f32_e32 v5, v80, v80
	v_max_f32_e32 v2, v65, v65
	v_min_f32_e32 v140, 0, v5
	v_min_f32_e32 v5, 0, v2
	v_pk_add_f32 v[182:183], v[4:5], v[0:1] neg_lo:[0,1] neg_hi:[0,1]
	v_exp_f32_e64 v0, -|v81|
	v_pk_add_f32 v[194:195], v[8:9], v[6:7] neg_lo:[0,1] neg_hi:[0,1]
	v_sub_f32_e32 v49, v183, v65
	v_sub_f32_e32 v14, v182, v64
	v_add_f32_e32 v0, 1.0, v0
	v_log_f32_e32 v139, v0
	v_max_f32_e32 v0, v81, v81
	v_min_f32_e32 v141, 0, v0
	v_sub_f32_e32 v15, v179, v63
	v_pk_add_f32 v[196:197], v[140:141], v[138:139] neg_lo:[0,1] neg_hi:[0,1]
	v_sub_f32_e32 v12, v178, v62
	v_sub_f32_e32 v11, v177, v61
	v_sub_f32_e32 v10, v176, v60
	v_sub_f32_e32 v13, v175, v59
	v_sub_f32_e32 v8, v174, v58
	v_sub_f32_e32 v7, v173, v57
	v_sub_f32_e32 v6, v172, v56
	v_sub_f32_e32 v9, v171, v55
	v_sub_f32_e32 v4, v170, v54
	v_sub_f32_e32 v5, v169, v53
	v_sub_f32_e32 v2, v168, v52
	v_sub_f32_e32 v1, v167, v51
	v_sub_f32_e32 v0, v166, v50
	v_sub_f32_e32 v65, v197, v81
	v_sub_f32_e32 v58, v196, v80
	v_sub_f32_e32 v63, v195, v79
	v_sub_f32_e32 v62, v194, v78
	v_sub_f32_e32 v61, v193, v77
	v_sub_f32_e32 v56, v192, v76
	v_sub_f32_e32 v59, v191, v75
	v_sub_f32_e32 v60, v190, v74
	v_sub_f32_e32 v57, v189, v73
	v_sub_f32_e32 v52, v188, v72
	v_sub_f32_e32 v55, v187, v71
	v_sub_f32_e32 v54, v186, v70
	v_sub_f32_e32 v53, v185, v69
	v_sub_f32_e32 v48, v184, v68
	v_sub_f32_e32 v51, v181, v67
	v_sub_f32_e32 v50, v180, v66
	s_and_saveexec_b64 s[90:91], vcc
	s_cbranch_execz .LBB0_582
; template <int TYPE>
; DI void attn_item(KargPtr p, int b, int h, int qb, unsigned char* smem) {
;     ...
;                 if (k0 + 63 >= qw) {
;                     asm volatile("");
;                     const int rel = myq - k0 - 4 * hh;
; #pragma unroll
;                     for (int i = 0; i < 16; ++i) {
;                         const int off = 8 * (i >> 2) + (i & 3);
;                         if (off >= rel) { lk0[i] = 0.f; s0[i] = -1e30f; }
;                         if (off + 32 >= rel) { lk1[i] = 0.f; s1[i] = -1e30f; }
;                     }
;                 }
	v_cmp_lt_i32_e64 s[68:69], 26, v223
	v_cmp_lt_i32_e64 s[70:71], 27, v223
	v_cmp_lt_i32_e64 s[66:67], 25, v223
	s_or_b64 s[68:69], s[70:71], s[68:69]
	v_cmp_lt_i32_e64 s[64:65], 24, v223
	s_or_b64 s[66:67], s[68:69], s[66:67]
	v_cmp_lt_i32_e64 s[62:63], 19, v223
	s_or_b64 s[64:65], s[66:67], s[64:65]
	v_cmp_lt_i32_e64 s[60:61], 18, v223
	s_or_b64 s[62:63], s[64:65], s[62:63]
	v_cmp_lt_i32_e64 s[58:59], 17, v223
	s_or_b64 s[60:61], s[62:63], s[60:61]
	v_cmp_lt_i32_e64 s[56:57], 16, v223
	s_or_b64 s[58:59], s[60:61], s[58:59]
	v_cmp_lt_i32_e64 s[54:55], 11, v223
	s_or_b64 s[56:57], s[58:59], s[56:57]
	v_cmp_lt_i32_e64 s[52:53], 10, v223
	s_or_b64 s[54:55], s[56:57], s[54:55]
	v_cmp_lt_i32_e64 s[50:51], 9, v223
	s_or_b64 s[52:53], s[54:55], s[52:53]
	v_cmp_lt_i32_e64 s[48:49], 8, v223
	s_or_b64 s[50:51], s[52:53], s[50:51]
	v_cmp_lt_i32_e64 s[46:47], 3, v223
	s_or_b64 s[48:49], s[50:51], s[48:49]
	v_cmp_lt_i32_e64 s[44:45], 2, v223
	s_or_b64 s[46:47], s[48:49], s[46:47]
	v_cmp_lt_i32_e64 s[42:43], 1, v223
	s_or_b64 s[44:45], s[46:47], s[44:45]
	v_cmp_lt_i32_e64 s[38:39], 0, v223
	s_or_b64 s[42:43], s[44:45], s[42:43]
	s_or_b64 s[38:39], s[42:43], s[38:39]
	v_cmp_lt_i32_e64 s[36:37], 58, v223
	v_cndmask_b32_e64 v0, 0, v0, s[38:39]
	v_cndmask_b32_e64 v166, v207, v166, s[38:39]
	v_cmp_lt_i32_e64 s[38:39], 59, v223
	v_cmp_lt_i32_e64 s[34:35], 57, v223
	s_or_b64 s[36:37], s[38:39], s[36:37]
	v_cmp_lt_i32_e64 s[30:31], 56, v223
	s_or_b64 s[34:35], s[36:37], s[34:35]
	v_cmp_lt_i32_e64 s[28:29], 51, v223
	s_or_b64 s[30:31], s[34:35], s[30:31]
	v_cmp_lt_i32_e64 s[26:27], 50, v223
	s_or_b64 s[28:29], s[30:31], s[28:29]
	v_cmp_lt_i32_e64 s[24:25], 49, v223
	s_or_b64 s[26:27], s[28:29], s[26:27]
	v_cmp_lt_i32_e64 s[22:23], 48, v223
	s_or_b64 s[24:25], s[26:27], s[24:25]
	v_cmp_lt_i32_e64 s[20:21], 43, v223
	s_or_b64 s[22:23], s[24:25], s[22:23]
	v_cmp_lt_i32_e64 s[18:19], 42, v223
	s_or_b64 s[20:21], s[22:23], s[20:21]
	v_cmp_lt_i32_e64 s[16:17], 41, v223
	s_or_b64 s[18:19], s[20:21], s[18:19]
	v_cmp_lt_i32_e64 s[14:15], 40, v223
	s_or_b64 s[16:17], s[18:19], s[16:17]
	v_cmp_lt_i32_e64 s[12:13], 35, v223
	s_or_b64 s[14:15], s[16:17], s[14:15]
	v_cmp_lt_i32_e64 s[10:11], 34, v223
	s_or_b64 s[12:13], s[14:15], s[12:13]
	v_cmp_lt_i32_e64 s[8:9], 33, v223
	s_or_b64 s[10:11], s[12:13], s[10:11]
	v_cmp_lt_i32_e32 vcc, 32, v223
	v_cndmask_b32_e64 v14, 0, v14, s[68:69]
	v_cndmask_b32_e64 v182, v207, v182, s[68:69]
	v_readlane_b32 s68, v254, 63
	s_or_b64 s[8:9], s[10:11], s[8:9]
	v_cndmask_b32_e64 v1, 0, v1, s[42:43]
	v_cndmask_b32_e64 v167, v207, v167, s[42:43]
	v_readlane_b32 s42, v255, 17
	v_readlane_b32 s69, v255, 0
	s_or_b64 vcc, s[8:9], vcc
	v_cndmask_b32_e64 v49, 0, v49, s[70:71]
	v_cndmask_b32_e64 v15, 0, v15, s[66:67]
	v_cndmask_b32_e64 v12, 0, v12, s[64:65]
	v_cndmask_b32_e64 v11, 0, v11, s[62:63]
	v_cndmask_b32_e64 v10, 0, v10, s[60:61]
	v_cndmask_b32_e64 v13, 0, v13, s[58:59]
	v_cndmask_b32_e64 v8, 0, v8, s[56:57]
	v_cndmask_b32_e64 v7, 0, v7, s[54:55]
	v_cndmask_b32_e64 v6, 0, v6, s[52:53]
	v_cndmask_b32_e64 v9, 0, v9, s[50:51]
	v_cndmask_b32_e64 v4, 0, v4, s[48:49]
	v_cndmask_b32_e64 v5, 0, v5, s[46:47]
	v_cndmask_b32_e64 v2, 0, v2, s[44:45]
	v_readlane_b32 s43, v255, 18
	v_cndmask_b32_e64 v168, v207, v168, s[44:45]
	v_cndmask_b32_e64 v169, v207, v169, s[46:47]
	v_cndmask_b32_e64 v170, v207, v170, s[48:49]
	v_cndmask_b32_e64 v171, v207, v171, s[50:51]
	v_cndmask_b32_e64 v172, v207, v172, s[52:53]
	v_cndmask_b32_e64 v173, v207, v173, s[54:55]
	v_cndmask_b32_e64 v174, v207, v174, s[56:57]
	v_cndmask_b32_e64 v175, v207, v175, s[58:59]
	v_cndmask_b32_e64 v176, v207, v176, s[60:61]
	v_readlane_b32 s61, v255, 19
	s_mov_b32 s60, 0xc32a0000
	v_cndmask_b32_e64 v177, v207, v177, s[62:63]
	s_movk_i32 s62, 0x1fff
	v_readlane_b32 s63, v255, 1
	v_cndmask_b32_e64 v178, v207, v178, s[64:65]
	s_mov_b32 s65, 0x10000
	v_readlane_b32 s64, v255, 2
	v_cndmask_b32_e64 v179, v207, v179, s[66:67]
	s_mov_b32 s67, 0x18000
	s_movk_i32 s66, 0x6000
	s_mov_b32 s69, 0x8000
	v_cndmask_b32_e64 v183, v207, v183, s[70:71]
	s_mov_b32 s71, 0x800000
	s_mov_b32 s70, 0x24000
	v_cndmask_b32_e64 v65, 0, v65, s[38:39]
	v_cndmask_b32_e64 v58, 0, v58, s[36:37]
	v_cndmask_b32_e64 v63, 0, v63, s[34:35]
	v_cndmask_b32_e64 v62, 0, v62, s[30:31]
	v_cndmask_b32_e64 v61, 0, v61, s[28:29]
	v_cndmask_b32_e64 v56, 0, v56, s[26:27]
	v_cndmask_b32_e64 v59, 0, v59, s[24:25]
	v_cndmask_b32_e64 v60, 0, v60, s[22:23]
	v_cndmask_b32_e64 v57, 0, v57, s[20:21]
	v_cndmask_b32_e64 v52, 0, v52, s[18:19]
	v_cndmask_b32_e64 v55, 0, v55, s[16:17]
	v_cndmask_b32_e64 v54, 0, v54, s[14:15]
	v_cndmask_b32_e64 v53, 0, v53, s[12:13]
	v_cndmask_b32_e64 v48, 0, v48, s[10:11]
	v_cndmask_b32_e64 v51, 0, v51, s[8:9]
	v_cndmask_b32_e32 v50, 0, v50, vcc
	v_cndmask_b32_e32 v180, v207, v180, vcc
	v_cndmask_b32_e64 v181, v207, v181, s[8:9]
	v_cndmask_b32_e64 v184, v207, v184, s[10:11]
	v_cndmask_b32_e64 v185, v207, v185, s[12:13]
	v_cndmask_b32_e64 v186, v207, v186, s[14:15]
	v_cndmask_b32_e64 v187, v207, v187, s[16:17]
	v_cndmask_b32_e64 v188, v207, v188, s[18:19]
	v_cndmask_b32_e64 v189, v207, v189, s[20:21]
	v_cndmask_b32_e64 v190, v207, v190, s[22:23]
	v_cndmask_b32_e64 v191, v207, v191, s[24:25]
	v_cndmask_b32_e64 v192, v207, v192, s[26:27]
	v_readlane_b32 s26, v255, 21
	v_cndmask_b32_e64 v193, v207, v193, s[28:29]
	v_cndmask_b32_e64 v194, v207, v194, s[30:31]
	s_mov_b32 s30, 0x3a800000
	v_cndmask_b32_e64 v195, v207, v195, s[34:35]
	v_cndmask_b32_e64 v196, v207, v196, s[36:37]
	s_mov_b32 s36, 0x358637bd
	v_cndmask_b32_e64 v197, v207, v197, s[38:39]
	s_mov_b64 s[38:39], 0x1000

; #define WAIT_OLD(S) do { if (TYPE == 2) asm volatile("s_waitcnt vmcnt(4)" : "+v"(rk0##S), "+v"(rk1##S), "+v"(rv0##S), "+v"(rv1##S), "+v"(rkr##S), "+v"(rck##S)); \
;         else asm volatile("s_waitcnt vmcnt(5)" : "+v"(rk0##S), "+v"(rk1##S), "+v"(rv0##S), "+v"(rv1##S), "+v"(rkr##S), "+v"(rck##S)); } while (0)
; #define SB_FLAGS(N_) do { if (TYPE != 1) { if (TYPE == 2) wdone = (__all(carry < -170.f) != 0); if (lane == 0) flags[((N_) & 1) * 8 + w8] = wdone ? 1u : 0u; } } while (0)
; template <int TYPE>
; DI void attn_item(KargPtr p, int b, int h, int qb, unsigned char* smem) {
;     ...
;         WAIT_OLD(B);
;         STORE_TILE(B, 0);
;         SB_FLAGS(n + 1);
;         __syncthreads();
;         if (SB_DONE(n + 1)) break;
;     }
.LBB0_583:
	s_or_b64 exec, exec, s[82:83]
	v_cmp_gt_f32_e32 vcc, s60, v164
	s_cmp_eq_u64 vcc, exec
	s_waitcnt vmcnt(4)
	s_cselect_b64 s[8:9], -1, 0
	ds_write_b128 v212, v[122:125]
	ds_write_b128 v213, v[126:129]
	ds_write2_b64 v215, v[130:131], v[132:133] offset0:128 offset1:130
	ds_write2_b64 v217, v[134:135], v[136:137] offset0:128 offset1:130
	s_and_saveexec_b64 s[10:11], s[6:7]
	v_cndmask_b32_e64 v0, 0, 1, s[8:9]
	ds_write_b32 v222, v0 offset:32
	s_or_b64 exec, exec, s[10:11]
	v_mov_b32_e32 v0, s96
	s_waitcnt lgkmcnt(0)
	s_barrier
	s_cmp_eq_u32 s3, 0
	s_cbranch_scc1 .Ldesync_2
	s_sleep 2
.Ldesync_2:
	ds_read_b128 v[4:7], v0
	v_mov_b32_e32 v1, s97
	s_xor_b64 s[10:11], s[88:89], -1
	s_addk_i32 s2, 0xff80
	v_add_u32_e32 v223, 0x80, v223
	s_waitcnt lgkmcnt(0)
	v_and_b32_e32 v0, v5, v4
	v_and_b32_e32 v0, v0, v6
	v_and_b32_e32 v0, v0, v7
	ds_read_b128 v[4:7], v1
	s_add_i32 s78, s33, -1
	s_waitcnt lgkmcnt(0)
	v_and_b32_e32 v0, v0, v4
	v_and_b32_e32 v0, v0, v5
	v_and_b32_e32 v0, v0, v6
	v_and_b32_e32 v0, v0, v7
	v_cmp_ne_u32_e32 vcc, 0, v0
	s_or_b64 s[10:11], vcc, s[10:11]
	s_and_b64 vcc, exec, s[10:11]
	s_cbranch_vccz .LBB0_572

; #define WAIT_OLD(S) do { if (TYPE == 2) asm volatile("s_waitcnt vmcnt(4)" : "+v"(rk0##S), "+v"(rk1##S), "+v"(rv0##S), "+v"(rv1##S), "+v"(rkr##S), "+v"(rck##S)); \
;         else asm volatile("s_waitcnt vmcnt(5)" : "+v"(rk0##S), "+v"(rk1##S), "+v"(rv0##S), "+v"(rv1##S), "+v"(rkr##S), "+v"(rck##S)); } while (0)
; #define SB_FLAGS(N_) do { if (TYPE != 1) { if (TYPE == 2) wdone = (__all(carry < -170.f) != 0); if (lane == 0) flags[((N_) & 1) * 8 + w8] = wdone ? 1u : 0u; } } while (0)
; template <int TYPE>
; DI void attn_item(KargPtr p, int b, int h, int qb, unsigned char* smem) {
;     ...
;         WAIT_OLD(A);
;         STORE_TILE(A, 1);
;         SB_FLAGS(n);
;         __syncthreads();
;         if (SB_DONE(n)) break;
;         if (n + 1 >= ntiles) break;
.LBB0_606:
	s_or_b64 exec, exec, s[10:11]
	v_mov_b32_e32 v0, s2
	s_waitcnt lgkmcnt(0)
	s_barrier
	s_cmp_eq_u32 s3, 0
	s_cbranch_scc1 .Ldesync_1
	s_sleep 2
.Ldesync_1:
	ds_read_b128 v[48:51], v0
	v_mov_b32_e32 v1, s97
	s_waitcnt lgkmcnt(0)
	v_and_b32_e32 v0, v49, v48
	v_and_b32_e32 v0, v0, v50
	v_and_b32_e32 v0, v0, v51
	ds_read_b128 v[48:51], v1
	s_waitcnt lgkmcnt(0)
	v_and_b32_e32 v0, v0, v48
	v_and_b32_e32 v0, v0, v49
	v_and_b32_e32 v0, v0, v50
	v_and_b32_e32 v0, v0, v51
	v_cmp_ne_u32_e32 vcc, 0, v0
	s_cbranch_vccz .LBB0_608
	s_cbranch_execz .LBB0_620
	s_branch .LBB0_564

; #define WAIT_OLD(S) do { if (TYPE == 2) asm volatile("s_waitcnt vmcnt(4)" : "+v"(rk0##S), "+v"(rk1##S), "+v"(rv0##S), "+v"(rv1##S), "+v"(rkr##S), "+v"(rck##S)); \
;         else asm volatile("s_waitcnt vmcnt(5)" : "+v"(rk0##S), "+v"(rk1##S), "+v"(rv0##S), "+v"(rv1##S), "+v"(rkr##S), "+v"(rck##S)); } while (0)
; #define SB_FLAGS(N_) do { if (TYPE != 1) { if (TYPE == 2) wdone = (__all(carry < -170.f) != 0); if (lane == 0) flags[((N_) & 1) * 8 + w8] = wdone ? 1u : 0u; } } while (0)
; template <int TYPE>
; DI void attn_item(KargPtr p, int b, int h, int qb, unsigned char* smem) {
;     ...
;         WAIT_OLD(B);
;         STORE_TILE(B, 0);
;         SB_FLAGS(n + 1);
;         __syncthreads();
;         if (SB_DONE(n + 1)) break;
.LBB0_617:
	s_or_b64 exec, exec, s[10:11]
	s_and_saveexec_b64 s[10:11], s[8:9]
	v_and_b32_e32 v0, 0xff, v189
	ds_write_b32 v187, v0 offset:32
	s_or_b64 exec, exec, s[10:11]
	v_mov_b32_e32 v0, s33
	s_waitcnt lgkmcnt(0)
	s_barrier
	s_cmp_eq_u32 s3, 0
	s_cbranch_scc1 .Ldesync_0
	s_sleep 2
.Ldesync_0:
	ds_read_b128 v[48:51], v0
	v_mov_b32_e32 v1, s79
	s_xor_b64 s[10:11], s[82:83], -1
	v_add_u32_e32 v188, 0x80, v188
	s_addk_i32 s74, 0xff80
	s_waitcnt lgkmcnt(0)
	v_and_b32_e32 v0, v49, v48
	v_and_b32_e32 v0, v0, v50
	v_and_b32_e32 v0, v0, v51
	ds_read_b128 v[48:51], v1
	s_add_i32 s84, s84, -1
	s_waitcnt lgkmcnt(0)
	v_and_b32_e32 v0, v0, v48
	v_and_b32_e32 v0, v0, v49
	v_and_b32_e32 v0, v0, v50
	v_and_b32_e32 v0, v0, v51
	v_cmp_ne_u32_e32 vcc, 0, v0
	s_or_b64 s[10:11], vcc, s[10:11]
	s_and_b64 vcc, exec, s[10:11]
	s_cbranch_vccnz .LBB0_564
